# phase0b down to 2 transposes per wave: items [3584,6416) (half of w_up + w_down weights) deferred to workgroups idle during the compress GEMM
# speedup vs baseline: 1.0156x; 1.0082x over previous
.LBB0_66:
	s_add_i32 s61, s61, s71
	s_add_i32 s14, s14, s15
	s_add_i32 s16, s16, s17
	s_add_i32 s18, s18, s19
	s_cmpk_lg_i32 s76, 0x100
	s_cbranch_scc1 .Lp0b_nocomp
	s_cmpk_gt_i32 s61, 0xfff
	s_cbranch_scc1 .LBB0_154
	s_cmpk_lt_i32 s61, 0xe00
	s_cbranch_scc1 .Lp0b_nocomp
	s_addk_i32 s61, 0xb10
	s_add_i32 s14, s14, 0x16200
	s_addk_i32 s16, 0x5880
	s_addk_i32 s18, 0x1620

.Ltail2_p0b:
	s_cmpk_lg_i32 s76, 0x100
	s_cbranch_scc1 .LBB0_371
	v_writelane_b32 v248, s20, 0
	v_writelane_b32 v248, s24, 1
	v_writelane_b32 v248, s25, 2
	v_writelane_b32 v248, s26, 3
	v_writelane_b32 v248, s27, 4
	v_writelane_b32 v248, s42, 5
	v_writelane_b32 v248, s44, 6
	v_writelane_b32 v248, s46, 7
	v_writelane_b32 v248, s47, 8
	v_writelane_b32 v248, s48, 9
	v_writelane_b32 v248, s49, 10
	v_writelane_b32 v248, s50, 11
	v_writelane_b32 v248, s54, 12
	v_writelane_b32 v248, s55, 13
	v_writelane_b32 v248, s56, 14
	s_add_i32 s2, 0, 0x23fa8
	v_mov_b32_e32 v0, s2
	ds_read_b64 v[2:3], v0
	v_mbcnt_lo_u32_b32 v0, -1, 0
	v_mbcnt_hi_u32_b32 v1, -1, v0
	s_waitcnt lgkmcnt(0)
	v_readfirstlane_b32 s0, v2
	v_readfirstlane_b32 s1, v3
	s_mov_b32 s3, 0
	v_readlane_b32 s61, v247, 1
	s_add_i32 s2, s80, 0xffffff80
	s_lshl_b32 s2, s2, 3
	s_lshr_b32 s61, s61, 6
	s_add_i32 s61, s61, s2
	s_addk_i32 s61, 0xe00
	s_cmpk_gt_i32 s61, 0x190f
	s_cbranch_scc1 .Ltail2_done
	s_lshl_b32 s2, s79, 14
	v_and_b32_e32 v0, 31, v1
	v_lshrrev_b32_e32 v18, 5, v1
	s_add_i32 s2, s2, 0
	v_lshlrev_b32_e32 v2, 2, v0
	v_mul_u32_u24_e32 v4, 0x84, v18
	v_add3_u32 v19, s2, v2, v4
	v_lshlrev_b32_e32 v2, 3, v1
	v_and_b32_e32 v2, 56, v2
	v_mov_b32_e32 v3, 0
	v_mul_u32_u24_e32 v8, 0x84, v2
	v_lshlrev_b32_e32 v2, 1, v2
	v_lshrrev_b32_e32 v20, 3, v1
	v_lshl_add_u64 v[4:5], s[0:1], 0, v[2:3]
	s_mov_b64 s[4:5], 0x1b00000
	v_lshl_add_u64 v[6:7], v[4:5], 0, s[4:5]
	v_lshlrev_b32_e32 v2, 2, v20
	s_mov_b64 s[4:5], 0x1a00000
	v_add3_u32 v21, s2, v8, v2
	v_lshl_add_u64 v[8:9], v[4:5], 0, s[4:5]
	s_mov_b64 s[4:5], 0x1400000
	v_lshl_add_u64 v[10:11], v[4:5], 0, s[4:5]
	s_mov_b64 s[4:5], 0x900000
	s_lshl_b32 s2, s61, 3
	v_lshl_add_u64 v[12:13], v[4:5], 0, s[4:5]
	s_mov_b64 s[4:5], 0x700000
	s_add_i32 s16, s2, 0x780
	s_lshl_b32 s2, s61, 1
	v_add_u32_e32 v22, 8, v20
	v_or_b32_e32 v23, 16, v20
	v_add_u32_e32 v24, 24, v20
	v_lshl_add_u64 v[14:15], v[4:5], 0, s[4:5]
	s_lshl_b32 s14, s61, 5
	s_mov_b32 s15, 0x8000
	s_movk_i32 s17, 0x2000
	s_add_i32 s18, s2, 0xffffd8e0
	s_movk_i32 s19, 0x800
	s_add_i32 s20, 0, 0x23f60
	s_mov_b64 s[4:5], 0x200000
	s_movk_i32 s21, 0x1000
	s_movk_i32 s24, 0x2000
	s_movk_i32 s25, 0x3000
	s_movk_i32 s26, 0x4000
	s_movk_i32 s27, 0x5000
	s_movk_i32 s28, 0x6000
	s_movk_i32 s29, 0x7000
	s_mov_b32 s30, 0x8000
	s_mov_b32 s31, 0x9000
	s_mov_b32 s33, 0xa000
	s_mov_b32 s34, 0xb000
	s_mov_b32 s35, 0xc000
	s_mov_b32 s36, 0xd000
	s_mov_b32 s37, 0xe000
	s_mov_b32 s38, 0xf000
	s_movk_i32 s39, 0x7fff
	s_mov_b32 s40, 0xffff0000
	s_add_i32 s41, 0, 0x23f98
	s_mov_b32 s42, 0x12000
	s_mov_b32 s43, 0x16000
	s_mov_b32 s44, 0x1a000
	s_mov_b32 s45, 0x1e000
	s_mov_b32 s46, 0x22000
	s_mov_b32 s47, 0x26000
	s_mov_b32 s48, 0x2a000
	s_mov_b32 s49, 0x2e000
	s_mov_b32 s50, 0x32000
	s_mov_b32 s51, 0x36000
	s_mov_b32 s52, 0x3a000
	s_mov_b32 s53, 0x3e000
	s_movk_i32 s54, 0x1600
	s_add_i32 s55, 0, 0x23f80
	s_movk_i32 s56, 0x5800
	s_add_i32 s57, 0, 0x23f70
	s_add_i32 s58, 0, 0x23f30
	s_movk_i32 s59, 0xd18
	s_movk_i32 s60, 0x3460
	v_lshlrev_b32_e32 v2, 2, v0
	v_add_u32_e32 v25, 0x400, v19
	v_add_u32_e32 v26, 0x800, v19
	v_add_u32_e32 v27, 0xc00, v19
	v_add_u32_e32 v28, 0x1000, v19
	v_add_u32_e32 v29, 0x1400, v19
	v_add_u32_e32 v30, 0x1800, v19
	v_add_u32_e32 v31, 0x1c00, v19
	s_branch .LBB0_67_u
